# OUT epilogue: 6 of 8 residual loads of the mi=1 half prefetched during the mi=0 half (both epi calls) into dead fragment registers
# baseline (speedup 1.0000x reference)
.LBB0_1003:
	s_barrier
	s_waitcnt vmcnt(9)
	ds_write_b128 v184, v[134:137]
	ds_write_b128 v184, v[142:145] offset:4608
	s_waitcnt vmcnt(8)
	ds_write_b128 v184, v[138:141] offset:9216
	s_waitcnt vmcnt(7)
	ds_write_b128 v184, v[150:153] offset:13824
	ds_write_b128 v184, v[130:133] offset:18432
	s_waitcnt vmcnt(6)
	ds_write_b128 v184, v[146:149] offset:23040
	s_waitcnt vmcnt(5)
	ds_write_b128 v184, v[154:157] offset:27648
	s_waitcnt vmcnt(4)
	ds_write_b128 v184, v[158:161] offset:32256
	s_waitcnt vmcnt(3)
	ds_write_b128 v184, v[162:165] offset:36864
	s_waitcnt vmcnt(2)
	ds_write_b128 v184, v[166:169] offset:41472
	s_waitcnt vmcnt(1)
	ds_write_b128 v184, v[170:173] offset:46080
	s_waitcnt vmcnt(0)
	ds_write_b128 v184, v[174:177] offset:50688
	s_waitcnt lgkmcnt(0)
	s_barrier
	s_setprio 2
	s_mov_b32 vcc_hi, 0
	ds_read_b128 v[244:247], v227
	ds_read_b128 v[210:213], v228 offset:18432
	ds_read_b128 v[248:251], v227 offset:4608
	ds_read_b128 v[214:217], v228 offset:23040
	ds_read_b128 v[218:221], v228 offset:27648
	ds_read_b128 v[222:225], v228 offset:32256
	s_waitcnt lgkmcnt(4)
	v_mfma_f32_32x32x16_bf16 v[114:129], v[210:213], v[244:247], v[114:129]
	s_add_u32 vcc_lo, s22, 0x80
	v_lshl_add_u64 v[238:239], v[194:195], 0, vcc
	global_load_dwordx4 v[130:133], v[238:239], off
	ds_read_b128 v[252:255], v227 offset:32
	s_waitcnt lgkmcnt(4)
	v_mfma_f32_32x32x16_bf16 v[82:97], v[210:213], v[248:251], v[82:97]
	s_add_u32 vcc_lo, s22, 0x80
	v_lshl_add_u64 v[178:179], v[192:193], 0, vcc
	global_load_dwordx4 v[134:137], v[178:179], off
	ds_read_b128 v[210:213], v228 offset:18464
	s_waitcnt lgkmcnt(4)
	v_mfma_f32_32x32x16_bf16 v[98:113], v[214:217], v[244:247], v[98:113]
	s_add_u32 vcc_lo, s22, 0x10080
	v_lshl_add_u64 v[238:239], v[192:193], 0, vcc
	global_load_dwordx4 v[142:145], v[238:239], off
	ds_read_b128 v[230:233], v227 offset:4640
	v_mfma_f32_32x32x16_bf16 v[66:81], v[214:217], v[248:251], v[66:81]
	s_add_u32 vcc_lo, s22, 0x20080
	v_lshl_add_u64 v[178:179], v[192:193], 0, vcc
	global_load_dwordx4 v[138:141], v[178:179], off
	ds_read_b128 v[214:217], v228 offset:23072
	s_waitcnt lgkmcnt(5)
	v_mfma_f32_32x32x16_bf16 v[50:65], v[218:221], v[244:247], v[50:65]
	s_add_u32 vcc_lo, s22, 0x30080
	v_lshl_add_u64 v[238:239], v[192:193], 0, vcc
	global_load_dwordx4 v[150:153], v[238:239], off
	v_mfma_f32_32x32x16_bf16 v[18:33], v[218:221], v[248:251], v[18:33]
	s_add_u32 vcc_lo, s22, 0x10080
	v_lshl_add_u64 v[178:179], v[194:195], 0, vcc
	global_load_dwordx4 v[146:149], v[178:179], off
	ds_read_b128 v[218:221], v228 offset:27680
	s_waitcnt lgkmcnt(5)
	v_mfma_f32_32x32x16_bf16 v[34:49], v[222:225], v[244:247], v[34:49]
	s_add_u32 vcc_lo, s22, 0x20080
	v_lshl_add_u64 v[238:239], v[194:195], 0, vcc
	global_load_dwordx4 v[154:157], v[238:239], off
	v_mfma_f32_32x32x16_bf16 v[2:17], v[222:225], v[248:251], v[2:17]
	s_add_u32 vcc_lo, s22, 0x30080
	v_lshl_add_u64 v[178:179], v[194:195], 0, vcc
	global_load_dwordx4 v[158:161], v[178:179], off
	ds_read_b128 v[222:225], v228 offset:32288
	s_waitcnt lgkmcnt(4)
	v_mfma_f32_32x32x16_bf16 v[114:129], v[210:213], v[252:255], v[114:129]
	s_add_u32 vcc_lo, s22, 0x40080
	v_lshl_add_u64 v[238:239], v[194:195], 0, vcc
	global_load_dwordx4 v[162:165], v[238:239], off
	ds_read_b128 v[244:247], v227 offset:64
	s_waitcnt lgkmcnt(4)
	v_mfma_f32_32x32x16_bf16 v[82:97], v[210:213], v[230:233], v[82:97]
	s_add_u32 vcc_lo, s22, 0x50080
	v_lshl_add_u64 v[178:179], v[194:195], 0, vcc
	global_load_dwordx4 v[166:169], v[178:179], off
	ds_read_b128 v[210:213], v228 offset:18496
	s_waitcnt lgkmcnt(4)
	v_mfma_f32_32x32x16_bf16 v[98:113], v[214:217], v[252:255], v[98:113]
	s_add_u32 vcc_lo, s22, 0x60080
	v_lshl_add_u64 v[238:239], v[194:195], 0, vcc
	global_load_dwordx4 v[170:173], v[238:239], off
	ds_read_b128 v[248:251], v227 offset:4672
	v_mfma_f32_32x32x16_bf16 v[66:81], v[214:217], v[230:233], v[66:81]
	s_add_u32 vcc_lo, s22, 0x70080
	v_lshl_add_u64 v[178:179], v[194:195], 0, vcc
	global_load_dwordx4 v[174:177], v[178:179], off
	ds_read_b128 v[214:217], v228 offset:23104
	s_waitcnt lgkmcnt(5)
	v_mfma_f32_32x32x16_bf16 v[50:65], v[218:221], v[252:255], v[50:65]
	v_mfma_f32_32x32x16_bf16 v[18:33], v[218:221], v[230:233], v[18:33]
	ds_read_b128 v[218:221], v228 offset:27712
	s_waitcnt lgkmcnt(5)
	v_mfma_f32_32x32x16_bf16 v[34:49], v[222:225], v[252:255], v[34:49]
	v_mfma_f32_32x32x16_bf16 v[2:17], v[222:225], v[230:233], v[2:17]
	ds_read_b128 v[222:225], v228 offset:32320
	s_waitcnt lgkmcnt(4)
	v_mfma_f32_32x32x16_bf16 v[114:129], v[210:213], v[244:247], v[114:129]
	ds_read_b128 v[252:255], v227 offset:96
	s_waitcnt lgkmcnt(4)
	v_mfma_f32_32x32x16_bf16 v[82:97], v[210:213], v[248:251], v[82:97]
	ds_read_b128 v[210:213], v228 offset:18528
	s_waitcnt lgkmcnt(4)
	v_mfma_f32_32x32x16_bf16 v[98:113], v[214:217], v[244:247], v[98:113]
	ds_read_b128 v[230:233], v227 offset:4704
	v_mfma_f32_32x32x16_bf16 v[66:81], v[214:217], v[248:251], v[66:81]
	ds_read_b128 v[214:217], v228 offset:23136
	s_waitcnt lgkmcnt(5)
	v_mfma_f32_32x32x16_bf16 v[50:65], v[218:221], v[244:247], v[50:65]
	v_mfma_f32_32x32x16_bf16 v[18:33], v[218:221], v[248:251], v[18:33]
	ds_read_b128 v[218:221], v228 offset:27744
	s_waitcnt lgkmcnt(5)
	v_mfma_f32_32x32x16_bf16 v[34:49], v[222:225], v[244:247], v[34:49]
	v_mfma_f32_32x32x16_bf16 v[2:17], v[222:225], v[248:251], v[2:17]
	ds_read_b128 v[222:225], v228 offset:32352
	s_waitcnt lgkmcnt(4)
	v_mfma_f32_32x32x16_bf16 v[114:129], v[210:213], v[252:255], v[114:129]
	s_waitcnt lgkmcnt(3)
	v_mfma_f32_32x32x16_bf16 v[82:97], v[210:213], v[230:233], v[82:97]
	s_waitcnt lgkmcnt(2)
	v_mfma_f32_32x32x16_bf16 v[98:113], v[214:217], v[252:255], v[98:113]
	v_mfma_f32_32x32x16_bf16 v[66:81], v[214:217], v[230:233], v[66:81]
	s_waitcnt lgkmcnt(1)
	v_mfma_f32_32x32x16_bf16 v[50:65], v[218:221], v[252:255], v[50:65]
	v_mfma_f32_32x32x16_bf16 v[18:33], v[218:221], v[230:233], v[18:33]
	s_waitcnt lgkmcnt(0)
	v_mfma_f32_32x32x16_bf16 v[34:49], v[222:225], v[252:255], v[34:49]
	v_mfma_f32_32x32x16_bf16 v[2:17], v[222:225], v[230:233], v[2:17]
	s_setprio 0
	s_add_u32 s22, s22, 0x80
	s_addc_u32 s23, s23, 0
	s_cmpk_eq_i32 s22, 0x780
	s_cbranch_scc0 .LBB0_1003
	v_mov_b32_e32 v210, 64
	v_xor_b32_e32 v211, 32, v209
	v_xor_b32_e32 v212, 16, v209
	v_xor_b32_e32 v213, 8, v209
	v_xor_b32_e32 v214, 4, v209
	v_xor_b32_e32 v215, 2, v209
	v_xor_b32_e32 v216, 1, v209
	v_mov_b32_e32 v217, 2
	v_bfrev_b32_e32 v218, 32
	v_bfrev_b32_e32 v219, 64
	v_mov_b32_e32 v220, 0xff800000
	v_mov_b32_e32 v221, 0x80
	v_mov_b32_e32 v222, 0x200
	v_mov_b32_e32 v223, 0x2000
	v_mov_b32_e32 v224, 0x461c4000
	v_mov_b32_e32 v225, 0x63
	v_mov_b64_e32 v[178:179], 0xf500000
	s_setprio 0
	s_barrier
	s_waitcnt vmcnt(10)
	ds_write_b128 v184, v[134:137]
	s_waitcnt vmcnt(9)
	ds_write_b128 v184, v[142:145] offset:4608
	s_waitcnt vmcnt(8)
	ds_write_b128 v184, v[138:141] offset:9216
	s_waitcnt vmcnt(7)
	ds_write_b128 v184, v[150:153] offset:13824
	ds_write_b128 v184, v[130:133] offset:18432
	s_waitcnt vmcnt(6)
	ds_write_b128 v184, v[146:149] offset:23040
	s_waitcnt vmcnt(5)
	ds_write_b128 v184, v[154:157] offset:27648
	s_waitcnt vmcnt(4)
	ds_write_b128 v184, v[158:161] offset:32256
	s_waitcnt vmcnt(3)
	ds_write_b128 v184, v[162:165] offset:36864
	s_waitcnt vmcnt(2)
	ds_write_b128 v184, v[166:169] offset:41472
	s_waitcnt vmcnt(1)
	ds_write_b128 v184, v[170:173] offset:46080
	s_waitcnt vmcnt(0)
	ds_write_b128 v184, v[174:177] offset:50688
	s_waitcnt lgkmcnt(0)
	s_setprio 0
	s_barrier
	s_setprio 1
	ds_read_b128 v[130:133], v227 offset:4608
	ds_read_b128 v[134:137], v228 offset:23040
	ds_read_b128 v[138:141], v227
	ds_read_b128 v[142:145], v227 offset:32
	ds_read_b128 v[146:149], v228 offset:18432
	ds_read_b128 v[150:153], v228 offset:18464
	s_waitcnt lgkmcnt(1)
	v_mfma_f32_32x32x16_bf16 v[114:129], v[146:149], v[138:141], v[114:129]
	v_add_u32_e32 v166, s2, v185
	v_or_b32_e32 v168, v166, v198
	v_ashrrev_i32_e32 v169, 31, v168
	v_cndmask_b32_e64 v167, 0, 1, s[42:43]
	v_cmp_ne_u32_e64 s[40:41], 1, v167
	s_andn2_b64 vcc, exec, s[42:43]
	v_mfma_f32_32x32x16_bf16 v[82:97], v[146:149], v[130:133], v[82:97]
	v_mfma_f32_32x32x16_bf16 v[98:113], v[134:137], v[138:141], v[98:113]
	v_mfma_f32_32x32x16_bf16 v[66:81], v[134:137], v[130:133], v[66:81]
	ds_read_b128 v[134:137], v228 offset:27648
	ds_read_b128 v[146:149], v228 offset:32256
	s_waitcnt lgkmcnt(1)
	v_mfma_f32_32x32x16_bf16 v[50:65], v[134:137], v[138:141], v[50:65]
	v_mfma_f32_32x32x16_bf16 v[18:33], v[134:137], v[130:133], v[18:33]
	s_waitcnt lgkmcnt(0)
	v_mfma_f32_32x32x16_bf16 v[2:17], v[146:149], v[130:133], v[2:17]
	ds_read_b128 v[130:133], v227 offset:4640
	ds_read_b128 v[134:137], v228 offset:23072
	v_mfma_f32_32x32x16_bf16 v[34:49], v[146:149], v[138:141], v[34:49]
	s_waitcnt lgkmcnt(0)
	v_mfma_f32_32x32x16_bf16 v[98:113], v[134:137], v[142:145], v[98:113]
	v_mfma_f32_32x32x16_bf16 v[66:81], v[134:137], v[130:133], v[66:81]
	ds_read_b128 v[134:137], v228 offset:27680
	ds_read_b128 v[138:141], v228 offset:32288
	v_mfma_f32_32x32x16_bf16 v[114:129], v[150:153], v[142:145], v[114:129]
	v_mfma_f32_32x32x16_bf16 v[82:97], v[150:153], v[130:133], v[82:97]
	v_lshlrev_b64 v[150:151], 10, v[168:169]
	s_waitcnt lgkmcnt(1)
	v_mfma_f32_32x32x16_bf16 v[50:65], v[134:137], v[142:145], v[50:65]
	v_mfma_f32_32x32x16_bf16 v[18:33], v[134:137], v[130:133], v[18:33]
	s_waitcnt lgkmcnt(0)
	v_mfma_f32_32x32x16_bf16 v[34:49], v[138:141], v[142:145], v[34:49]
	v_mfma_f32_32x32x16_bf16 v[2:17], v[138:141], v[130:133], v[2:17]
	ds_read_b128 v[130:133], v227 offset:64
	ds_read_b128 v[134:137], v227 offset:4672
	ds_read_b128 v[138:141], v228 offset:18496
	ds_read_b128 v[142:145], v228 offset:23104
	s_waitcnt lgkmcnt(1)
	v_mfma_f32_32x32x16_bf16 v[114:129], v[138:141], v[130:133], v[114:129]
	v_mfma_f32_32x32x16_bf16 v[82:97], v[138:141], v[134:137], v[82:97]
	s_waitcnt lgkmcnt(0)
	v_mfma_f32_32x32x16_bf16 v[98:113], v[142:145], v[130:133], v[98:113]
	v_mfma_f32_32x32x16_bf16 v[66:81], v[142:145], v[134:137], v[66:81]
	ds_read_b128 v[138:141], v228 offset:27712
	ds_read_b128 v[142:145], v228 offset:32320
	s_waitcnt lgkmcnt(1)
	v_mfma_f32_32x32x16_bf16 v[50:65], v[138:141], v[130:133], v[50:65]
	v_mfma_f32_32x32x16_bf16 v[18:33], v[138:141], v[134:137], v[18:33]
	s_waitcnt lgkmcnt(0)
	v_mfma_f32_32x32x16_bf16 v[34:49], v[142:145], v[130:133], v[34:49]
	v_mfma_f32_32x32x16_bf16 v[2:17], v[142:145], v[134:137], v[2:17]
	ds_read_b128 v[130:133], v227 offset:96
	ds_read_b128 v[134:137], v227 offset:4704
	ds_read_b128 v[138:141], v228 offset:18528
	ds_read_b128 v[142:145], v228 offset:23136
	s_waitcnt lgkmcnt(1)
	v_mfma_f32_32x32x16_bf16 v[114:129], v[138:141], v[130:133], v[114:129]
	v_mfma_f32_32x32x16_bf16 v[82:97], v[138:141], v[134:137], v[82:97]
	s_waitcnt lgkmcnt(0)
	v_mfma_f32_32x32x16_bf16 v[98:113], v[142:145], v[130:133], v[98:113]
	v_mfma_f32_32x32x16_bf16 v[66:81], v[142:145], v[134:137], v[66:81]
	ds_read_b128 v[138:141], v228 offset:27744
	ds_read_b128 v[142:145], v228 offset:32352
	s_waitcnt lgkmcnt(0)
	s_setprio 0
	s_barrier
	v_mfma_f32_32x32x16_bf16 v[50:65], v[138:141], v[130:133], v[50:65]
	v_mfma_f32_32x32x16_bf16 v[34:49], v[142:145], v[130:133], v[34:49]
	v_ashrrev_i32_e32 v132, 11, v166
	v_add_u32_e32 v0, s8, v132
	v_mov_b64_e32 v[130:131], s[46:47]
	v_mfma_f32_32x32x16_bf16 v[18:33], v[138:141], v[134:137], v[18:33]
	v_or_b32_e32 v138, s3, v197
	v_mad_i64_i32 v[130:131], s[2:3], v0, s20, v[130:131]
	s_mov_b64 s[2:3], 0xc902000
	v_ashrrev_i32_e32 v139, 31, v138
	v_lshl_add_u64 v[140:141], v[130:131], 0, s[2:3]
	v_lshlrev_b32_e32 v0, 2, v186
	v_mfma_f32_32x32x16_bf16 v[2:17], v[142:145], v[134:137], v[2:17]
	v_lshlrev_b64 v[144:145], 2, v[138:139]
	v_lshl_add_u64 v[130:131], v[140:141], 0, v[144:145]
	v_lshl_add_u64 v[130:131], v[130:131], 0, v[0:1]
	global_load_dwordx4 v[134:137], v[130:131], off
	v_lshlrev_b32_e32 v130, 10, v132
	v_ashrrev_i32_e32 v131, 31, v130
	v_lshl_add_u64 v[130:131], v[130:131], 2, s[36:37]
	v_lshl_add_u64 v[130:131], v[130:131], 0, v[144:145]
	v_lshl_add_u64 v[142:143], v[130:131], 0, v[0:1]
	global_load_dwordx4 v[130:133], v[142:143], off
	ds_write_b128 v199, v[114:117]
	ds_write_b128 v199, v[118:121] offset:32
	ds_write_b128 v199, v[122:125] offset:64
	ds_write_b128 v199, v[126:129] offset:96
	ds_write_b128 v199, v[98:101] offset:128
	ds_write_b128 v199, v[102:105] offset:160
	ds_write_b128 v199, v[106:109] offset:192
	ds_write_b128 v199, v[110:113] offset:224
	v_lshl_add_u64 v[170:171], v[188:189], 0, v[144:145]
	v_lshlrev_b64 v[98:99], 12, v[168:169]
	v_lshl_add_u64 v[144:145], v[170:171], 0, v[98:99]
	v_or_b32_e32 v98, 4, v168
	v_ashrrev_i32_e32 v99, 31, v98
	v_lshlrev_b64 v[98:99], 12, v[98:99]
	v_lshl_add_u64 v[146:147], v[170:171], 0, v[98:99]
	v_or_b32_e32 v98, 8, v168
	v_ashrrev_i32_e32 v99, 31, v98
	v_lshlrev_b64 v[98:99], 12, v[98:99]
	v_lshl_add_u64 v[148:149], v[170:171], 0, v[98:99]
	v_or_b32_e32 v98, 12, v168
	v_ashrrev_i32_e32 v99, 31, v98
	v_lshlrev_b64 v[98:99], 12, v[98:99]
	v_lshl_add_u64 v[152:153], v[170:171], 0, v[98:99]
	v_or_b32_e32 v98, 16, v168
	v_ashrrev_i32_e32 v99, 31, v98
	v_lshlrev_b64 v[98:99], 12, v[98:99]
	v_lshl_add_u64 v[156:157], v[170:171], 0, v[98:99]
	v_or_b32_e32 v98, 20, v168
	v_ashrrev_i32_e32 v99, 31, v98
	v_lshlrev_b64 v[98:99], 12, v[98:99]
	v_lshl_add_u64 v[158:159], v[170:171], 0, v[98:99]
	v_or_b32_e32 v98, 24, v168
	v_ashrrev_i32_e32 v99, 31, v98
	v_lshlrev_b64 v[98:99], 12, v[98:99]
	v_lshl_add_u64 v[160:161], v[170:171], 0, v[98:99]
	v_or_b32_e32 v98, 28, v168
	v_ashrrev_i32_e32 v99, 31, v98
	v_lshlrev_b64 v[98:99], 12, v[98:99]
	global_load_dwordx4 v[126:129], v[144:145], off
	global_load_dwordx4 v[122:125], v[146:147], off
	v_lshl_add_u64 v[162:163], v[170:171], 0, v[98:99]
	global_load_dwordx4 v[118:121], v[148:149], off
	global_load_dwordx4 v[114:117], v[152:153], off
	global_load_dwordx4 v[110:113], v[156:157], off
	global_load_dwordx4 v[106:109], v[158:159], off
	global_load_dwordx4 v[102:105], v[160:161], off
	global_load_dwordx4 v[98:101], v[162:163], off
	s_mov_b64 s[2:3], 0x20000
	v_lshl_add_u64 v[230:231], v[144:145], 0, s[2:3]
	global_load_dwordx4 v[230:233], v[230:231], off
	v_lshl_add_u64 v[234:235], v[146:147], 0, s[2:3]
	global_load_dwordx4 v[234:237], v[234:235], off
	v_lshl_add_u64 v[238:239], v[148:149], 0, s[2:3]
	global_load_dwordx4 v[238:241], v[238:239], off
	v_lshl_add_u64 v[244:245], v[152:153], 0, s[2:3]
	global_load_dwordx4 v[244:247], v[244:245], off
	v_lshl_add_u64 v[248:249], v[156:157], 0, s[2:3]
	global_load_dwordx4 v[248:251], v[248:249], off
	v_lshl_add_u64 v[252:253], v[158:159], 0, s[2:3]
	global_load_dwordx4 v[252:255], v[252:253], off
	ds_read_b128 v[172:175], v229
	v_or_b32_e32 v164, v138, v186
	v_mov_b32_e32 v165, v139
	v_lshl_add_u64 v[154:155], v[150:151], 0, v[164:165]
	s_mov_b64 s[2:3], -1
	s_waitcnt vmcnt(13) lgkmcnt(0)
	v_pk_fma_f32 v[128:129], v[136:137], v[174:175], v[128:129]
	v_pk_fma_f32 v[126:127], v[134:135], v[172:173], v[126:127]
	v_lshl_add_u64 v[172:173], v[154:155], 2, s[44:45]
	global_store_dwordx4 v[172:173], v[126:129], off
	s_cbranch_vccnz .LBB0_1006
	s_mov_b64 s[2:3], 0

.LBB0_1010:
	s_or_b64 exec, exec, s[2:3]
	ds_read_b128 v[192:195], v229 offset:1088
	v_or_b32_e32 v128, v166, v200
	s_waitcnt lgkmcnt(1)
	v_ashrrev_i32_e32 v129, 31, v128
	v_lshlrev_b64 v[154:155], 10, v[128:129]
	v_lshl_add_u64 v[128:129], v[154:155], 0, v[164:165]
	s_waitcnt vmcnt(13) lgkmcnt(0)
	v_pk_fma_f32 v[124:125], v[136:137], v[194:195], v[124:125]
	v_pk_fma_f32 v[122:123], v[134:135], v[192:193], v[122:123]
	v_lshl_add_u64 v[176:177], v[128:129], 2, s[44:45]
	s_and_b64 vcc, exec, s[40:41]
	s_mov_b64 s[2:3], -1
	global_store_dwordx4 v[176:177], v[122:125], off
	s_cbranch_vccnz .LBB0_1012
	s_mov_b64 s[2:3], 0

.LBB0_1016:
	s_or_b64 exec, exec, s[2:3]
	ds_read_b128 v[192:195], v229 offset:2176
	v_or_b32_e32 v122, v166, v201
	s_waitcnt lgkmcnt(1)
	v_ashrrev_i32_e32 v123, 31, v122
	v_lshlrev_b64 v[128:129], 10, v[122:123]
	v_lshl_add_u64 v[122:123], v[128:129], 0, v[164:165]
	s_waitcnt vmcnt(13) lgkmcnt(0)
	v_pk_fma_f32 v[120:121], v[136:137], v[194:195], v[120:121]
	v_pk_fma_f32 v[118:119], v[134:135], v[192:193], v[118:119]
	v_lshl_add_u64 v[124:125], v[122:123], 2, s[44:45]
	s_and_b64 vcc, exec, s[40:41]
	s_mov_b64 s[2:3], -1
	global_store_dwordx4 v[124:125], v[118:121], off
	s_cbranch_vccnz .LBB0_1018
	s_mov_b64 s[2:3], 0

.LBB0_1022:
	s_or_b64 exec, exec, s[2:3]
	ds_read_b128 v[122:125], v229 offset:3264
	v_or_b32_e32 v118, v166, v202
	s_waitcnt lgkmcnt(1)
	v_ashrrev_i32_e32 v119, 31, v118
	v_lshlrev_b64 v[120:121], 10, v[118:119]
	v_lshl_add_u64 v[118:119], v[120:121], 0, v[164:165]
	s_waitcnt vmcnt(13) lgkmcnt(0)
	v_pk_fma_f32 v[116:117], v[136:137], v[124:125], v[116:117]
	v_pk_fma_f32 v[114:115], v[134:135], v[122:123], v[114:115]
	v_lshl_add_u64 v[122:123], v[118:119], 2, s[44:45]
	s_and_b64 vcc, exec, s[40:41]
	s_mov_b64 s[2:3], -1
	global_store_dwordx4 v[122:123], v[114:117], off
	s_cbranch_vccnz .LBB0_1024
	s_mov_b64 s[2:3], 0

.LBB0_1028:
	s_or_b64 exec, exec, s[2:3]
	ds_read_b128 v[122:125], v229 offset:4352
	v_or_b32_e32 v114, v166, v203
	s_waitcnt lgkmcnt(1)
	v_ashrrev_i32_e32 v115, 31, v114
	v_lshlrev_b64 v[114:115], 10, v[114:115]
	v_lshl_add_u64 v[116:117], v[114:115], 0, v[164:165]
	s_waitcnt vmcnt(13) lgkmcnt(0)
	v_pk_fma_f32 v[112:113], v[136:137], v[124:125], v[112:113]
	v_pk_fma_f32 v[110:111], v[134:135], v[122:123], v[110:111]
	v_lshl_add_u64 v[118:119], v[116:117], 2, s[44:45]
	s_and_b64 vcc, exec, s[40:41]
	s_mov_b64 s[2:3], -1
	global_store_dwordx4 v[118:119], v[110:113], off
	s_cbranch_vccnz .LBB0_1030
	s_mov_b64 s[2:3], 0

.LBB0_1034:
	s_or_b64 exec, exec, s[2:3]
	ds_read_b128 v[116:119], v229 offset:5440
	v_or_b32_e32 v110, v166, v204
	s_waitcnt lgkmcnt(1)
	v_ashrrev_i32_e32 v111, 31, v110
	v_lshlrev_b64 v[110:111], 10, v[110:111]
	v_lshl_add_u64 v[112:113], v[110:111], 0, v[164:165]
	s_waitcnt vmcnt(13) lgkmcnt(0)
	v_pk_fma_f32 v[108:109], v[136:137], v[118:119], v[108:109]
	v_pk_fma_f32 v[106:107], v[134:135], v[116:117], v[106:107]
	v_lshl_add_u64 v[116:117], v[112:113], 2, s[44:45]
	s_and_b64 vcc, exec, s[40:41]
	s_mov_b64 s[2:3], -1
	global_store_dwordx4 v[116:117], v[106:109], off
	s_cbranch_vccnz .LBB0_1036
	s_mov_b64 s[2:3], 0

.LBB0_1040:
	s_or_b64 exec, exec, s[2:3]
	ds_read_b128 v[116:119], v229 offset:6528
	v_or_b32_e32 v106, v166, v205
	s_waitcnt lgkmcnt(1)
	v_ashrrev_i32_e32 v107, 31, v106
	v_lshlrev_b64 v[106:107], 10, v[106:107]
	v_lshl_add_u64 v[108:109], v[106:107], 0, v[164:165]
	s_waitcnt vmcnt(13) lgkmcnt(0)
	v_pk_fma_f32 v[104:105], v[136:137], v[118:119], v[104:105]
	v_pk_fma_f32 v[102:103], v[134:135], v[116:117], v[102:103]
	v_lshl_add_u64 v[112:113], v[108:109], 2, s[44:45]
	s_and_b64 vcc, exec, s[40:41]
	s_mov_b64 s[2:3], -1
	global_store_dwordx4 v[112:113], v[102:105], off
	s_cbranch_vccnz .LBB0_1042
	s_mov_b64 s[2:3], 0

.LBB0_1046:
	s_or_b64 exec, exec, s[2:3]
	ds_read_b128 v[116:119], v229 offset:7616
	v_or_b32_e32 v102, v166, v226
	s_waitcnt lgkmcnt(1)
	v_ashrrev_i32_e32 v103, 31, v102
	v_lshlrev_b64 v[102:103], 10, v[102:103]
	v_lshl_add_u64 v[104:105], v[102:103], 0, v[164:165]
	s_waitcnt vmcnt(13) lgkmcnt(0)
	v_pk_fma_f32 v[100:101], v[136:137], v[118:119], v[100:101]
	v_pk_fma_f32 v[98:99], v[134:135], v[116:117], v[98:99]
	v_lshl_add_u64 v[108:109], v[104:105], 2, s[44:45]
	s_and_b64 vcc, exec, s[40:41]
	s_mov_b64 s[2:3], -1
	global_store_dwordx4 v[108:109], v[98:101], off
	s_cbranch_vccnz .LBB0_1048
	s_mov_b64 s[2:3], 0

.LBB0_1052:
	s_or_b64 exec, exec, s[2:3]
	ds_write_b128 v199, v[82:85]
	ds_write_b128 v199, v[86:89] offset:32
	ds_write_b128 v199, v[90:93] offset:64
	ds_write_b128 v199, v[94:97] offset:96
	ds_write_b128 v199, v[66:69] offset:128
	ds_write_b128 v199, v[70:73] offset:160
	ds_write_b128 v199, v[74:77] offset:192
	ds_write_b128 v199, v[78:81] offset:224
	v_or_b32_e32 v66, 32, v168
	v_ashrrev_i32_e32 v67, 31, v66
	v_lshlrev_b64 v[66:67], 12, v[66:67]
	s_waitcnt lgkmcnt(8)
	v_lshl_add_u64 v[98:99], v[170:171], 0, v[66:67]
	v_or_b32_e32 v66, 36, v168
	v_ashrrev_i32_e32 v67, 31, v66
	v_lshlrev_b64 v[66:67], 12, v[66:67]
	v_lshl_add_u64 v[100:101], v[170:171], 0, v[66:67]
	v_or_b32_e32 v66, 40, v168
	v_ashrrev_i32_e32 v67, 31, v66
	v_lshlrev_b64 v[66:67], 12, v[66:67]
	v_lshl_add_u64 v[108:109], v[170:171], 0, v[66:67]
	v_or_b32_e32 v66, 44, v168
	v_ashrrev_i32_e32 v67, 31, v66
	v_lshlrev_b64 v[66:67], 12, v[66:67]
	v_lshl_add_u64 v[112:113], v[170:171], 0, v[66:67]
	v_or_b32_e32 v66, 48, v168
	v_ashrrev_i32_e32 v67, 31, v66
	v_lshlrev_b64 v[66:67], 12, v[66:67]
	v_lshl_add_u64 v[116:117], v[170:171], 0, v[66:67]
	v_or_b32_e32 v66, 52, v168
	v_ashrrev_i32_e32 v67, 31, v66
	v_lshlrev_b64 v[66:67], 12, v[66:67]
	v_lshl_add_u64 v[118:119], v[170:171], 0, v[66:67]
	v_or_b32_e32 v66, 56, v168
	v_ashrrev_i32_e32 v67, 31, v66
	v_lshlrev_b64 v[66:67], 12, v[66:67]
	v_lshl_add_u64 v[122:123], v[170:171], 0, v[66:67]
	v_or_b32_e32 v66, 60, v168
	v_ashrrev_i32_e32 v67, 31, v66
	v_lshlrev_b64 v[66:67], 12, v[66:67]
	v_lshl_add_u64 v[124:125], v[170:171], 0, v[66:67]
	s_waitcnt vmcnt(8)
	v_mov_b64_e32 v[94:95], v[230:231]
	v_mov_b64_e32 v[96:97], v[232:233]
	v_mov_b64_e32 v[90:91], v[234:235]
	v_mov_b64_e32 v[92:93], v[236:237]
	v_mov_b64_e32 v[86:87], v[238:239]
	v_mov_b64_e32 v[88:89], v[240:241]
	v_mov_b64_e32 v[82:83], v[244:245]
	v_mov_b64_e32 v[84:85], v[246:247]
	v_mov_b64_e32 v[78:79], v[248:249]
	v_mov_b64_e32 v[80:81], v[250:251]
	v_mov_b64_e32 v[74:75], v[252:253]
	v_mov_b64_e32 v[76:77], v[254:255]
	global_load_dwordx4 v[70:73], v[122:123], off
	global_load_dwordx4 v[66:69], v[124:125], off
	v_or_b32_e32 v168, 32, v166
	ds_read_b128 v[192:195], v229
	v_or_b32_e32 v104, v168, v198
	v_ashrrev_i32_e32 v105, 31, v104
	v_lshlrev_b64 v[104:105], 10, v[104:105]
	v_lshl_add_u64 v[166:167], v[104:105], 0, v[164:165]
	v_lshl_add_u64 v[170:171], v[166:167], 2, s[44:45]
	s_mov_b64 s[2:3], -1
	s_and_b64 vcc, exec, s[40:41]
	s_waitcnt lgkmcnt(0)
	v_pk_fma_f32 v[96:97], v[136:137], v[194:195], v[96:97]
	v_pk_fma_f32 v[94:95], v[134:135], v[192:193], v[94:95]
	global_store_dwordx4 v[170:171], v[94:97], off
	s_cbranch_vccnz .LBB0_1054
	s_mov_b64 s[2:3], 0

.LBB0_1058:
	s_or_b64 exec, exec, s[2:3]
	ds_read_b128 v[192:195], v229 offset:1088
	v_or_b32_e32 v94, v168, v200
	s_waitcnt lgkmcnt(1)
	v_ashrrev_i32_e32 v95, 31, v94
	v_lshlrev_b64 v[94:95], 10, v[94:95]
	v_lshl_add_u64 v[96:97], v[94:95], 0, v[164:165]
	s_waitcnt lgkmcnt(0)
	v_pk_fma_f32 v[92:93], v[136:137], v[194:195], v[92:93]
	v_pk_fma_f32 v[90:91], v[134:135], v[192:193], v[90:91]
	v_lshl_add_u64 v[166:167], v[96:97], 2, s[44:45]
	s_and_b64 vcc, exec, s[40:41]
	s_mov_b64 s[2:3], -1
	global_store_dwordx4 v[166:167], v[90:93], off
	s_cbranch_vccnz .LBB0_1060
	s_mov_b64 s[2:3], 0

.LBB0_1064:
	s_or_b64 exec, exec, s[2:3]
	ds_read_b128 v[192:195], v229 offset:2176
	v_or_b32_e32 v90, v168, v201
	s_waitcnt lgkmcnt(1)
	v_ashrrev_i32_e32 v91, 31, v90
	v_lshlrev_b64 v[90:91], 10, v[90:91]
	v_lshl_add_u64 v[92:93], v[90:91], 0, v[164:165]
	s_waitcnt lgkmcnt(0)
	v_pk_fma_f32 v[88:89], v[136:137], v[194:195], v[88:89]
	v_pk_fma_f32 v[86:87], v[134:135], v[192:193], v[86:87]
	v_lshl_add_u64 v[96:97], v[92:93], 2, s[44:45]
	s_and_b64 vcc, exec, s[40:41]
	s_mov_b64 s[2:3], -1
	global_store_dwordx4 v[96:97], v[86:89], off
	s_cbranch_vccnz .LBB0_1066
	s_mov_b64 s[2:3], 0

.LBB0_1070:
	s_or_b64 exec, exec, s[2:3]
	ds_read_b128 v[192:195], v229 offset:3264
	v_or_b32_e32 v86, v168, v202
	s_waitcnt lgkmcnt(1)
	v_ashrrev_i32_e32 v87, 31, v86
	v_lshlrev_b64 v[86:87], 10, v[86:87]
	v_lshl_add_u64 v[88:89], v[86:87], 0, v[164:165]
	s_waitcnt lgkmcnt(0)
	v_pk_fma_f32 v[84:85], v[136:137], v[194:195], v[84:85]
	v_pk_fma_f32 v[82:83], v[134:135], v[192:193], v[82:83]
	v_lshl_add_u64 v[92:93], v[88:89], 2, s[44:45]
	s_and_b64 vcc, exec, s[40:41]
	s_mov_b64 s[2:3], -1
	global_store_dwordx4 v[92:93], v[82:85], off
	s_cbranch_vccnz .LBB0_1072
	s_mov_b64 s[2:3], 0

.LBB0_1076:
	s_or_b64 exec, exec, s[2:3]
	ds_read_b128 v[192:195], v229 offset:4352
	v_or_b32_e32 v82, v168, v203
	s_waitcnt lgkmcnt(1)
	v_ashrrev_i32_e32 v83, 31, v82
	v_lshlrev_b64 v[82:83], 10, v[82:83]
	v_lshl_add_u64 v[84:85], v[82:83], 0, v[164:165]
	s_waitcnt lgkmcnt(0)
	v_pk_fma_f32 v[80:81], v[136:137], v[194:195], v[80:81]
	v_pk_fma_f32 v[78:79], v[134:135], v[192:193], v[78:79]
	v_lshl_add_u64 v[88:89], v[84:85], 2, s[44:45]
	s_and_b64 vcc, exec, s[40:41]
	s_mov_b64 s[2:3], -1
	global_store_dwordx4 v[88:89], v[78:81], off
	s_cbranch_vccnz .LBB0_1078
	s_mov_b64 s[2:3], 0

.LBB0_1082:
	s_or_b64 exec, exec, s[2:3]
	ds_read_b128 v[192:195], v229 offset:5440
	v_or_b32_e32 v78, v168, v204
	s_waitcnt lgkmcnt(1)
	v_ashrrev_i32_e32 v79, 31, v78
	v_lshlrev_b64 v[78:79], 10, v[78:79]
	v_lshl_add_u64 v[80:81], v[78:79], 0, v[164:165]
	s_waitcnt lgkmcnt(0)
	v_pk_fma_f32 v[76:77], v[136:137], v[194:195], v[76:77]
	v_pk_fma_f32 v[74:75], v[134:135], v[192:193], v[74:75]
	v_lshl_add_u64 v[84:85], v[80:81], 2, s[44:45]
	s_and_b64 vcc, exec, s[40:41]
	s_mov_b64 s[2:3], -1
	global_store_dwordx4 v[84:85], v[74:77], off
	s_cbranch_vccnz .LBB0_1084
	s_mov_b64 s[2:3], 0

.LBB0_1100:
	s_or_b64 exec, exec, s[2:3]
	v_or_b32_e32 v80, 64, v138
	v_ashrrev_i32_e32 v81, 31, v80
	s_waitcnt lgkmcnt(0)
	v_lshl_add_u64 v[66:67], v[140:141], 0, v[0:1]
	v_lshl_add_u64 v[66:67], v[80:81], 2, v[66:67]
	global_load_dwordx4 v[70:73], v[66:67], off
	s_nop 0
	global_load_dwordx4 v[66:69], v[142:143], off offset:256
	ds_write_b128 v199, v[50:53]
	ds_write_b128 v199, v[54:57] offset:32
	ds_write_b128 v199, v[58:61] offset:64
	ds_write_b128 v199, v[62:65] offset:96
	ds_write_b128 v199, v[34:37] offset:128
	ds_write_b128 v199, v[38:41] offset:160
	ds_write_b128 v199, v[42:45] offset:192
	ds_write_b128 v199, v[46:49] offset:224
	global_load_dwordx4 v[62:65], v[144:145], off offset:256
	global_load_dwordx4 v[58:61], v[146:147], off offset:256
	global_load_dwordx4 v[54:57], v[148:149], off offset:256
	global_load_dwordx4 v[50:53], v[152:153], off offset:256
	global_load_dwordx4 v[46:49], v[156:157], off offset:256
	global_load_dwordx4 v[42:45], v[158:159], off offset:256
	global_load_dwordx4 v[38:41], v[160:161], off offset:256
	global_load_dwordx4 v[34:37], v[162:163], off offset:256
	global_load_dwordx4 v[230:233], v[98:99], off offset:256
	global_load_dwordx4 v[234:237], v[100:101], off offset:256
	global_load_dwordx4 v[238:241], v[108:109], off offset:256
	global_load_dwordx4 v[244:247], v[112:113], off offset:256
	global_load_dwordx4 v[248:251], v[116:117], off offset:256
	global_load_dwordx4 v[252:255], v[118:119], off offset:256
	ds_read_b128 v[130:133], v229
	v_lshl_add_u64 v[84:85], v[138:139], 0, v[186:187]
	v_lshl_add_u64 v[88:89], v[150:151], 0, v[84:85]
	s_and_b64 vcc, exec, s[40:41]
	v_lshl_add_u64 v[88:89], v[88:89], 2, s[44:45]
	s_mov_b64 s[2:3], -1
	s_waitcnt vmcnt(13) lgkmcnt(0)
	v_pk_fma_f32 v[64:65], v[72:73], v[132:133], v[64:65]
	v_pk_fma_f32 v[62:63], v[70:71], v[130:131], v[62:63]
	global_store_dwordx4 v[88:89], v[62:65], off offset:256
	s_cbranch_vccnz .LBB0_1102
	s_mov_b64 s[2:3], 0

.LBB0_1106:
	s_or_b64 exec, exec, s[2:3]
	s_waitcnt lgkmcnt(0)
	ds_read_b128 v[62:65], v229 offset:1088
	s_mov_b64 s[2:3], -1
	s_and_b64 vcc, exec, s[40:41]
	s_waitcnt vmcnt(13) lgkmcnt(0)
	v_pk_fma_f32 v[58:59], v[70:71], v[62:63], v[58:59]
	v_lshl_add_u64 v[62:63], v[154:155], 0, v[84:85]
	v_pk_fma_f32 v[60:61], v[72:73], v[64:65], v[60:61]
	v_lshl_add_u64 v[62:63], v[62:63], 2, s[44:45]
	global_store_dwordx4 v[62:63], v[58:61], off offset:256
	s_cbranch_vccnz .LBB0_1108
	s_mov_b64 s[2:3], 0

.LBB0_1112:
	s_or_b64 exec, exec, s[2:3]
	s_waitcnt lgkmcnt(0)
	ds_read_b128 v[58:61], v229 offset:2176
	s_mov_b64 s[2:3], -1
	s_and_b64 vcc, exec, s[40:41]
	s_waitcnt vmcnt(13) lgkmcnt(0)
	v_pk_fma_f32 v[54:55], v[70:71], v[58:59], v[54:55]
	v_lshl_add_u64 v[58:59], v[128:129], 0, v[84:85]
	v_pk_fma_f32 v[56:57], v[72:73], v[60:61], v[56:57]
	v_lshl_add_u64 v[58:59], v[58:59], 2, s[44:45]
	global_store_dwordx4 v[58:59], v[54:57], off offset:256
	s_cbranch_vccnz .LBB0_1114
	s_mov_b64 s[2:3], 0

.LBB0_1118:
	s_or_b64 exec, exec, s[2:3]
	s_waitcnt lgkmcnt(0)
	ds_read_b128 v[54:57], v229 offset:3264
	s_mov_b64 s[2:3], -1
	s_and_b64 vcc, exec, s[40:41]
	s_waitcnt vmcnt(13) lgkmcnt(0)
	v_pk_fma_f32 v[50:51], v[70:71], v[54:55], v[50:51]
	v_lshl_add_u64 v[54:55], v[120:121], 0, v[84:85]
	v_pk_fma_f32 v[52:53], v[72:73], v[56:57], v[52:53]
	v_lshl_add_u64 v[54:55], v[54:55], 2, s[44:45]
	global_store_dwordx4 v[54:55], v[50:53], off offset:256
	s_cbranch_vccnz .LBB0_1120
	s_mov_b64 s[2:3], 0

.LBB0_1124:
	s_or_b64 exec, exec, s[2:3]
	s_waitcnt lgkmcnt(0)
	ds_read_b128 v[50:53], v229 offset:4352
	s_mov_b64 s[2:3], -1
	s_and_b64 vcc, exec, s[40:41]
	s_waitcnt vmcnt(13) lgkmcnt(0)
	v_pk_fma_f32 v[46:47], v[70:71], v[50:51], v[46:47]
	v_lshl_add_u64 v[50:51], v[114:115], 0, v[84:85]
	v_pk_fma_f32 v[48:49], v[72:73], v[52:53], v[48:49]
	v_lshl_add_u64 v[50:51], v[50:51], 2, s[44:45]
	global_store_dwordx4 v[50:51], v[46:49], off offset:256
	s_cbranch_vccnz .LBB0_1126
	s_mov_b64 s[2:3], 0

.LBB0_1130:
	s_or_b64 exec, exec, s[2:3]
	s_waitcnt lgkmcnt(0)
	ds_read_b128 v[46:49], v229 offset:5440
	s_mov_b64 s[2:3], -1
	s_and_b64 vcc, exec, s[40:41]
	s_waitcnt vmcnt(13) lgkmcnt(0)
	v_pk_fma_f32 v[42:43], v[70:71], v[46:47], v[42:43]
	v_lshl_add_u64 v[46:47], v[110:111], 0, v[84:85]
	v_pk_fma_f32 v[44:45], v[72:73], v[48:49], v[44:45]
	v_lshl_add_u64 v[46:47], v[46:47], 2, s[44:45]
	global_store_dwordx4 v[46:47], v[42:45], off offset:256
	s_cbranch_vccnz .LBB0_1132
	s_mov_b64 s[2:3], 0

.LBB0_1136:
	s_or_b64 exec, exec, s[2:3]
	s_waitcnt lgkmcnt(0)
	ds_read_b128 v[42:45], v229 offset:6528
	s_mov_b64 s[2:3], -1
	s_and_b64 vcc, exec, s[40:41]
	s_waitcnt vmcnt(13) lgkmcnt(0)
	v_pk_fma_f32 v[38:39], v[70:71], v[42:43], v[38:39]
	v_lshl_add_u64 v[42:43], v[106:107], 0, v[84:85]
	v_pk_fma_f32 v[40:41], v[72:73], v[44:45], v[40:41]
	v_lshl_add_u64 v[42:43], v[42:43], 2, s[44:45]
	global_store_dwordx4 v[42:43], v[38:41], off offset:256
	s_cbranch_vccnz .LBB0_1138
	s_mov_b64 s[2:3], 0

.LBB0_1142:
	s_or_b64 exec, exec, s[2:3]
	s_waitcnt lgkmcnt(0)
	ds_read_b128 v[38:41], v229 offset:7616
	s_mov_b64 s[2:3], -1
	s_and_b64 vcc, exec, s[40:41]
	s_waitcnt vmcnt(13) lgkmcnt(0)
	v_pk_fma_f32 v[34:35], v[70:71], v[38:39], v[34:35]
	v_lshl_add_u64 v[38:39], v[102:103], 0, v[84:85]
	v_pk_fma_f32 v[36:37], v[72:73], v[40:41], v[36:37]
	v_lshl_add_u64 v[38:39], v[38:39], 2, s[44:45]
	global_store_dwordx4 v[38:39], v[34:37], off offset:256
	s_cbranch_vccnz .LBB0_1144
	s_mov_b64 s[2:3], 0

.LBB0_1148:
	s_or_b64 exec, exec, s[2:3]
	ds_write_b128 v199, v[18:21]
	ds_write_b128 v199, v[22:25] offset:32
	ds_write_b128 v199, v[26:29] offset:64
	ds_write_b128 v199, v[30:33] offset:96
	ds_write_b128 v199, v[2:5] offset:128
	ds_write_b128 v199, v[6:9] offset:160
	ds_write_b128 v199, v[10:13] offset:192
	ds_write_b128 v199, v[14:17] offset:224
	s_waitcnt vmcnt(8)
	v_mov_b64_e32 v[30:31], v[230:231]
	v_mov_b64_e32 v[32:33], v[232:233]
	v_mov_b64_e32 v[26:27], v[234:235]
	v_mov_b64_e32 v[28:29], v[236:237]
	v_mov_b64_e32 v[22:23], v[238:239]
	v_mov_b64_e32 v[24:25], v[240:241]
	v_mov_b64_e32 v[18:19], v[244:245]
	v_mov_b64_e32 v[20:21], v[246:247]
	v_mov_b64_e32 v[14:15], v[248:249]
	v_mov_b64_e32 v[16:17], v[250:251]
	v_mov_b64_e32 v[10:11], v[252:253]
	v_mov_b64_e32 v[12:13], v[254:255]
	global_load_dwordx4 v[6:9], v[122:123], off offset:256
	global_load_dwordx4 v[2:5], v[124:125], off offset:256
	s_waitcnt lgkmcnt(8)
	ds_read_b128 v[34:37], v229
	v_lshl_add_u64 v[38:39], v[104:105], 0, v[84:85]
	s_and_b64 vcc, exec, s[40:41]
	v_lshl_add_u64 v[38:39], v[38:39], 2, s[44:45]
	s_mov_b64 s[2:3], -1
	s_waitcnt lgkmcnt(0)
	v_pk_fma_f32 v[32:33], v[72:73], v[36:37], v[32:33]
	v_pk_fma_f32 v[30:31], v[70:71], v[34:35], v[30:31]
	global_store_dwordx4 v[38:39], v[30:33], off offset:256
	s_cbranch_vccnz .LBB0_1150
	s_mov_b64 s[2:3], 0

.LBB0_1154:
	s_or_b64 exec, exec, s[2:3]
	s_waitcnt lgkmcnt(0)
	ds_read_b128 v[30:33], v229 offset:1088
	s_mov_b64 s[2:3], -1
	s_and_b64 vcc, exec, s[40:41]
	s_waitcnt lgkmcnt(0)
	v_pk_fma_f32 v[26:27], v[70:71], v[30:31], v[26:27]
	v_lshl_add_u64 v[30:31], v[94:95], 0, v[84:85]
	v_pk_fma_f32 v[28:29], v[72:73], v[32:33], v[28:29]
	v_lshl_add_u64 v[30:31], v[30:31], 2, s[44:45]
	global_store_dwordx4 v[30:31], v[26:29], off offset:256
	s_cbranch_vccnz .LBB0_1156
	s_mov_b64 s[2:3], 0

.LBB0_1160:
	s_or_b64 exec, exec, s[2:3]
	s_waitcnt lgkmcnt(0)
	ds_read_b128 v[26:29], v229 offset:2176
	s_mov_b64 s[2:3], -1
	s_and_b64 vcc, exec, s[40:41]
	s_waitcnt lgkmcnt(0)
	v_pk_fma_f32 v[22:23], v[70:71], v[26:27], v[22:23]
	v_lshl_add_u64 v[26:27], v[90:91], 0, v[84:85]
	v_pk_fma_f32 v[24:25], v[72:73], v[28:29], v[24:25]
	v_lshl_add_u64 v[26:27], v[26:27], 2, s[44:45]
	global_store_dwordx4 v[26:27], v[22:25], off offset:256
	s_cbranch_vccnz .LBB0_1162
	s_mov_b64 s[2:3], 0

.LBB0_1166:
	s_or_b64 exec, exec, s[2:3]
	s_waitcnt lgkmcnt(0)
	ds_read_b128 v[22:25], v229 offset:3264
	s_mov_b64 s[2:3], -1
	s_and_b64 vcc, exec, s[40:41]
	s_waitcnt lgkmcnt(0)
	v_pk_fma_f32 v[18:19], v[70:71], v[22:23], v[18:19]
	v_lshl_add_u64 v[22:23], v[86:87], 0, v[84:85]
	v_pk_fma_f32 v[20:21], v[72:73], v[24:25], v[20:21]
	v_lshl_add_u64 v[22:23], v[22:23], 2, s[44:45]
	global_store_dwordx4 v[22:23], v[18:21], off offset:256
	s_cbranch_vccnz .LBB0_1168
	s_mov_b64 s[2:3], 0

.LBB0_1172:
	s_or_b64 exec, exec, s[2:3]
	s_waitcnt lgkmcnt(0)
	ds_read_b128 v[18:21], v229 offset:4352
	s_mov_b64 s[2:3], -1
	s_and_b64 vcc, exec, s[40:41]
	s_waitcnt lgkmcnt(0)
	v_pk_fma_f32 v[14:15], v[70:71], v[18:19], v[14:15]
	v_lshl_add_u64 v[18:19], v[82:83], 0, v[84:85]
	v_pk_fma_f32 v[16:17], v[72:73], v[20:21], v[16:17]
	v_lshl_add_u64 v[18:19], v[18:19], 2, s[44:45]
	global_store_dwordx4 v[18:19], v[14:17], off offset:256
	s_cbranch_vccnz .LBB0_1174
	s_mov_b64 s[2:3], 0

.LBB0_1178:
	s_or_b64 exec, exec, s[2:3]
	s_waitcnt lgkmcnt(0)
	ds_read_b128 v[14:17], v229 offset:5440
	s_mov_b64 s[2:3], -1
	s_and_b64 vcc, exec, s[40:41]
	s_waitcnt lgkmcnt(0)
	v_pk_fma_f32 v[10:11], v[70:71], v[14:15], v[10:11]
	v_lshl_add_u64 v[14:15], v[78:79], 0, v[84:85]
	v_pk_fma_f32 v[12:13], v[72:73], v[16:17], v[12:13]
	v_lshl_add_u64 v[14:15], v[14:15], 2, s[44:45]
	global_store_dwordx4 v[14:15], v[10:13], off offset:256
	s_cbranch_vccnz .LBB0_1180
	s_mov_b64 s[2:3], 0
